# E_RES GEMM epilogues (FFN2 and MLA w_o) de-serialized: row stats loaded once, all x loads of a column group in flight with counted vmcnt, registers refilled right after each store (baseline: load-wait
# speedup vs baseline: 1.1512x; 1.0133x over previous
.LBB0_832:
	s_add_i32 s72, s36, 0x400
	v_lshrrev_b32_e32 v0, 4, v133
	v_add3_u32 v133, s72, v136, v135
	v_add3_u32 v218, s39, v137, v135
	s_setprio 3
	ds_read_b128 v[134:137], v218
	ds_read_b128 v[138:141], v218 offset:2048
	ds_read_b128 v[142:145], v218 offset:4096
	ds_read_b128 v[146:149], v218 offset:6144
	ds_read_b128 v[150:153], v133
	ds_read_b128 v[154:157], v133 offset:2048
	ds_read_b128 v[158:161], v133 offset:4096
	ds_read_b128 v[166:169], v133 offset:6144
	ds_read_b128 v[170:173], v133 offset:8192
	s_waitcnt lgkmcnt(4)
	v_mfma_f32_16x16x32_bf16 v[126:129], v[134:137], v[150:153], v[126:129]
	v_mfma_f32_16x16x32_bf16 v[122:125], v[138:141], v[150:153], v[122:125]
	v_mfma_f32_16x16x32_bf16 v[118:121], v[142:145], v[150:153], v[118:121]
	v_mfma_f32_16x16x32_bf16 v[114:117], v[146:149], v[150:153], v[114:117]
	ds_read_b128 v[150:153], v133 offset:10240
	s_waitcnt lgkmcnt(4)
	v_mfma_f32_16x16x32_bf16 v[110:113], v[134:137], v[154:157], v[110:113]
	v_mfma_f32_16x16x32_bf16 v[106:109], v[138:141], v[154:157], v[106:109]
	v_mfma_f32_16x16x32_bf16 v[102:105], v[142:145], v[154:157], v[102:105]
	v_mfma_f32_16x16x32_bf16 v[98:101], v[146:149], v[154:157], v[98:101]
	ds_read_b128 v[154:157], v133 offset:12288
	s_waitcnt lgkmcnt(4)
	v_mfma_f32_16x16x32_bf16 v[174:177], v[134:137], v[158:161], v[94:97]
	v_mfma_f32_16x16x32_bf16 v[186:189], v[138:141], v[158:161], v[90:93]
	v_mfma_f32_16x16x32_bf16 v[190:193], v[142:145], v[158:161], v[86:89]
	v_mfma_f32_16x16x32_bf16 v[82:85], v[146:149], v[158:161], v[82:85]
	s_nop 1
	ds_read_b128 v[86:89], v133 offset:14336
	s_waitcnt lgkmcnt(4)
	v_mfma_f32_16x16x32_bf16 v[78:81], v[134:137], v[166:169], v[78:81]
	v_mfma_f32_16x16x32_bf16 v[74:77], v[138:141], v[166:169], v[74:77]
	v_mfma_f32_16x16x32_bf16 v[70:73], v[142:145], v[166:169], v[70:73]
	v_mfma_f32_16x16x32_bf16 v[66:69], v[146:149], v[166:169], v[66:69]
	s_waitcnt lgkmcnt(3)
	v_mfma_f32_16x16x32_bf16 v[158:161], v[134:137], v[170:173], v[62:65]
	v_mfma_f32_16x16x32_bf16 v[166:169], v[138:141], v[170:173], v[58:61]
	v_mfma_f32_16x16x32_bf16 v[194:197], v[142:145], v[170:173], v[54:57]
	v_mfma_f32_16x16x32_bf16 v[170:173], v[146:149], v[170:173], v[50:53]
	s_waitcnt lgkmcnt(2)
	v_mfma_f32_16x16x32_bf16 v[198:201], v[134:137], v[150:153], v[46:49]
	v_mfma_f32_16x16x32_bf16 v[42:45], v[138:141], v[150:153], v[42:45]
	v_mfma_f32_16x16x32_bf16 v[38:41], v[142:145], v[150:153], v[38:41]
	v_mfma_f32_16x16x32_bf16 v[34:37], v[146:149], v[150:153], v[34:37]
	s_waitcnt lgkmcnt(1)
	v_mfma_f32_16x16x32_bf16 v[150:153], v[134:137], v[154:157], v[30:33]
	v_mfma_f32_16x16x32_bf16 v[202:205], v[138:141], v[154:157], v[26:29]
	v_mfma_f32_16x16x32_bf16 v[206:209], v[142:145], v[154:157], v[22:25]
	v_mfma_f32_16x16x32_bf16 v[154:157], v[146:149], v[154:157], v[18:21]
	s_waitcnt lgkmcnt(0)
	v_mfma_f32_16x16x32_bf16 v[134:137], v[134:137], v[86:89], v[14:17]
	v_mfma_f32_16x16x32_bf16 v[138:141], v[138:141], v[86:89], v[10:13]
	v_mfma_f32_16x16x32_bf16 v[142:145], v[142:145], v[86:89], v[6:9]
	v_mfma_f32_16x16x32_bf16 v[2:5], v[146:149], v[86:89], v[2:5]
	s_setprio 0
	s_setprio 3
	ds_read_b128 v[146:149], v218 offset:1024
	ds_read_b128 v[210:213], v218 offset:3072
	ds_read_b128 v[214:217], v218 offset:5120
	ds_read_b128 v[218:221], v218 offset:7168
	ds_read_b128 v[6:9], v133 offset:1024
	ds_read_b128 v[10:13], v133 offset:3072
	ds_read_b128 v[14:17], v133 offset:5120
	ds_read_b128 v[18:21], v133 offset:7168
	ds_read_b128 v[222:225], v133 offset:9216
	s_waitcnt lgkmcnt(4)
	v_mfma_f32_16x16x32_bf16 v[226:229], v[146:149], v[6:9], v[126:129]
	v_mfma_f32_16x16x32_bf16 v[94:97], v[210:213], v[6:9], v[122:125]
	v_mfma_f32_16x16x32_bf16 v[62:65], v[214:217], v[6:9], v[118:121]
	v_mfma_f32_16x16x32_bf16 v[30:33], v[218:221], v[6:9], v[114:117]
	ds_read_b128 v[6:9], v133 offset:11264
	s_waitcnt lgkmcnt(4)
	v_mfma_f32_16x16x32_bf16 v[230:233], v[146:149], v[10:13], v[110:113]
	v_mfma_f32_16x16x32_bf16 v[90:93], v[210:213], v[10:13], v[106:109]
	v_mfma_f32_16x16x32_bf16 v[58:61], v[214:217], v[10:13], v[102:105]
	v_mfma_f32_16x16x32_bf16 v[26:29], v[218:221], v[10:13], v[98:101]
	s_nop 2
	ds_read_b128 v[98:101], v133 offset:13312
	s_waitcnt lgkmcnt(4)
	v_mfma_f32_16x16x32_bf16 v[174:177], v[146:149], v[14:17], v[174:177]
	v_mfma_f32_16x16x32_bf16 v[86:89], v[210:213], v[14:17], v[186:189]
	v_mfma_f32_16x16x32_bf16 v[54:57], v[214:217], v[14:17], v[190:193]
	v_mfma_f32_16x16x32_bf16 v[22:25], v[218:221], v[14:17], v[82:85]
	ds_read_b128 v[114:117], v133 offset:15360
	s_waitcnt lgkmcnt(4)
	v_mfma_f32_16x16x32_bf16 v[118:121], v[146:149], v[18:21], v[78:81]
	v_mfma_f32_16x16x32_bf16 v[82:85], v[210:213], v[18:21], v[74:77]
	v_mfma_f32_16x16x32_bf16 v[50:53], v[214:217], v[18:21], v[70:73]
	v_mfma_f32_16x16x32_bf16 v[18:21], v[218:221], v[18:21], v[66:69]
	s_waitcnt lgkmcnt(3)
	v_mfma_f32_16x16x32_bf16 v[110:113], v[146:149], v[222:225], v[158:161]
	v_mfma_f32_16x16x32_bf16 v[78:81], v[210:213], v[222:225], v[166:169]
	v_mfma_f32_16x16x32_bf16 v[46:49], v[214:217], v[222:225], v[194:197]
	v_mfma_f32_16x16x32_bf16 v[14:17], v[218:221], v[222:225], v[170:173]
	s_waitcnt lgkmcnt(2)
	v_mfma_f32_16x16x32_bf16 v[106:109], v[146:149], v[6:9], v[198:201]
	v_mfma_f32_16x16x32_bf16 v[74:77], v[210:213], v[6:9], v[42:45]
	v_mfma_f32_16x16x32_bf16 v[42:45], v[214:217], v[6:9], v[38:41]
	v_mfma_f32_16x16x32_bf16 v[10:13], v[218:221], v[6:9], v[34:37]
	s_waitcnt lgkmcnt(1)
	v_mfma_f32_16x16x32_bf16 v[102:105], v[146:149], v[98:101], v[150:153]
	v_mfma_f32_16x16x32_bf16 v[70:73], v[210:213], v[98:101], v[202:205]
	v_mfma_f32_16x16x32_bf16 v[38:41], v[214:217], v[98:101], v[206:209]
	v_mfma_f32_16x16x32_bf16 v[6:9], v[218:221], v[98:101], v[154:157]
	s_waitcnt lgkmcnt(0)
	v_mfma_f32_16x16x32_bf16 v[98:101], v[146:149], v[114:117], v[134:137]
	v_mfma_f32_16x16x32_bf16 v[66:69], v[210:213], v[114:117], v[138:141]
	v_mfma_f32_16x16x32_bf16 v[34:37], v[214:217], v[114:117], v[142:145]
	v_mfma_f32_16x16x32_bf16 v[2:5], v[218:221], v[114:117], v[2:5]
	s_setprio 0
	v_lshlrev_b32_e32 v115, 7, v130
	s_waitcnt vmcnt(0)
	s_barrier
	v_lshl_or_b32 v114, v132, 6, s88
	v_add3_u32 v144, v115, s80, v131
	v_lshl_add_u32 v128, v0, 2, v114
	v_lshlrev_b32_e32 v129, 12, v144
	v_lshl_add_u32 v129, v128, 2, v129
	v_add_u32_e32 v145, 0x10000, v129
	v_add_u32_e32 v210, 0x20000, v129
	v_add_u32_e32 v211, 0x30000, v129
	v_add_u32_e32 v212, 0x40000, v129
	v_add_u32_e32 v213, 0x50000, v129
	v_add_u32_e32 v214, 0x60000, v129
	v_add_u32_e32 v215, 0x70000, v129
	v_lshlrev_b32_e32 v216, 2, v128
	v_lshlrev_b32_e32 v217, 3, v144
	global_load_dwordx2 v[126:127], v217, s[8:9]
	global_load_dwordx2 v[142:143], v217, s[8:9] offset:128
	global_load_dwordx2 v[158:159], v217, s[8:9] offset:256
	global_load_dwordx2 v[160:161], v217, s[8:9] offset:384
	global_load_dwordx2 v[166:167], v217, s[8:9] offset:512
	global_load_dwordx2 v[168:169], v217, s[8:9] offset:640
	global_load_dwordx2 v[170:171], v217, s[8:9] offset:768
	global_load_dwordx2 v[172:173], v217, s[8:9] offset:896
	global_load_dwordx4 v[186:189], v216, s[6:7]
	global_load_dwordx4 v[190:193], v216, s[84:85]
	global_load_dwordx4 v[194:197], v216, s[86:87]
	global_load_dwordx4 v[114:117], v129, s[82:83]
	global_load_dwordx4 v[122:125], v145, s[82:83]
	global_load_dwordx4 v[130:133], v210, s[82:83]
	global_load_dwordx4 v[134:137], v211, s[82:83]
	global_load_dwordx4 v[138:141], v212, s[82:83]
	global_load_dwordx4 v[146:149], v213, s[82:83]
	global_load_dwordx4 v[150:153], v214, s[82:83]
	global_load_dwordx4 v[154:157], v215, s[82:83]
	global_load_dwordx4 v[198:201], v216, s[6:7] offset:64
	global_load_dwordx4 v[202:205], v216, s[84:85] offset:64
	global_load_dwordx4 v[206:209], v216, s[86:87] offset:64
	s_waitcnt vmcnt(11)
	v_pk_mul_f32 v[190:191], v[190:191], s[70:71] op_sel_hi:[1,0]
	v_pk_mul_f32 v[192:193], v[192:193], s[70:71] op_sel_hi:[1,0]
	v_pk_mul_f32 v[194:195], v[194:195], s[70:71] op_sel_hi:[1,0]
	v_pk_mul_f32 v[196:197], v[196:197], s[70:71] op_sel_hi:[1,0]
	s_waitcnt vmcnt(10)
	v_pk_add_f32 v[114:115], v[114:115], v[126:127] op_sel_hi:[1,0] neg_lo:[0,1] neg_hi:[0,1]
	v_pk_add_f32 v[116:117], v[116:117], v[126:127] op_sel_hi:[1,0] neg_lo:[0,1] neg_hi:[0,1]
	v_pk_mul_f32 v[114:115], v[114:115], v[126:127] op_sel:[0,1]
	v_pk_mul_f32 v[116:117], v[116:117], v[126:127] op_sel:[0,1]
	v_pk_fma_f32 v[114:115], v[190:191], v[114:115], v[194:195]
	v_pk_fma_f32 v[116:117], v[192:193], v[116:117], v[196:197]
	v_pk_fma_f32 v[114:115], v[226:227], v[186:187], v[114:115]
	v_pk_fma_f32 v[116:117], v[228:229], v[188:189], v[116:117]
	global_store_dwordx4 v129, v[114:117], s[4:5]
	s_nop 1
	global_load_dwordx4 v[114:117], v129, s[82:83] offset:64
	s_waitcnt vmcnt(11)
	v_pk_add_f32 v[122:123], v[122:123], v[142:143] op_sel_hi:[1,0] neg_lo:[0,1] neg_hi:[0,1]
	v_pk_add_f32 v[124:125], v[124:125], v[142:143] op_sel_hi:[1,0] neg_lo:[0,1] neg_hi:[0,1]
	v_pk_mul_f32 v[122:123], v[122:123], v[142:143] op_sel:[0,1]
	v_pk_mul_f32 v[124:125], v[124:125], v[142:143] op_sel:[0,1]
	v_pk_fma_f32 v[122:123], v[190:191], v[122:123], v[194:195]
	v_pk_fma_f32 v[124:125], v[192:193], v[124:125], v[196:197]
	v_pk_fma_f32 v[122:123], v[230:231], v[186:187], v[122:123]
	v_pk_fma_f32 v[124:125], v[232:233], v[188:189], v[124:125]
	global_store_dwordx4 v145, v[122:125], s[4:5]
	s_nop 1
	global_load_dwordx4 v[122:125], v145, s[82:83] offset:64
	s_waitcnt vmcnt(12)
	v_pk_add_f32 v[130:131], v[130:131], v[158:159] op_sel_hi:[1,0] neg_lo:[0,1] neg_hi:[0,1]
	v_pk_add_f32 v[132:133], v[132:133], v[158:159] op_sel_hi:[1,0] neg_lo:[0,1] neg_hi:[0,1]
	v_pk_mul_f32 v[130:131], v[130:131], v[158:159] op_sel:[0,1]
	v_pk_mul_f32 v[132:133], v[132:133], v[158:159] op_sel:[0,1]
	v_pk_fma_f32 v[130:131], v[190:191], v[130:131], v[194:195]
	v_pk_fma_f32 v[132:133], v[192:193], v[132:133], v[196:197]
	v_pk_fma_f32 v[130:131], v[174:175], v[186:187], v[130:131]
	v_pk_fma_f32 v[132:133], v[176:177], v[188:189], v[132:133]
	global_store_dwordx4 v210, v[130:133], s[4:5]
	s_nop 1
	global_load_dwordx4 v[130:133], v210, s[82:83] offset:64
	s_waitcnt vmcnt(13)
	v_pk_add_f32 v[134:135], v[134:135], v[160:161] op_sel_hi:[1,0] neg_lo:[0,1] neg_hi:[0,1]
	v_pk_add_f32 v[136:137], v[136:137], v[160:161] op_sel_hi:[1,0] neg_lo:[0,1] neg_hi:[0,1]
	v_pk_mul_f32 v[134:135], v[134:135], v[160:161] op_sel:[0,1]
	v_pk_mul_f32 v[136:137], v[136:137], v[160:161] op_sel:[0,1]
	v_pk_fma_f32 v[134:135], v[190:191], v[134:135], v[194:195]
	v_pk_fma_f32 v[136:137], v[192:193], v[136:137], v[196:197]
	v_pk_fma_f32 v[134:135], v[118:119], v[186:187], v[134:135]
	v_pk_fma_f32 v[136:137], v[120:121], v[188:189], v[136:137]
	global_store_dwordx4 v211, v[134:137], s[4:5]
	s_nop 1
	global_load_dwordx4 v[134:137], v211, s[82:83] offset:64
	s_waitcnt vmcnt(14)
	v_pk_add_f32 v[138:139], v[138:139], v[166:167] op_sel_hi:[1,0] neg_lo:[0,1] neg_hi:[0,1]
	v_pk_add_f32 v[140:141], v[140:141], v[166:167] op_sel_hi:[1,0] neg_lo:[0,1] neg_hi:[0,1]
	v_pk_mul_f32 v[138:139], v[138:139], v[166:167] op_sel:[0,1]
	v_pk_mul_f32 v[140:141], v[140:141], v[166:167] op_sel:[0,1]
	v_pk_fma_f32 v[138:139], v[190:191], v[138:139], v[194:195]
	v_pk_fma_f32 v[140:141], v[192:193], v[140:141], v[196:197]
	v_pk_fma_f32 v[138:139], v[110:111], v[186:187], v[138:139]
	v_pk_fma_f32 v[140:141], v[112:113], v[188:189], v[140:141]
	global_store_dwordx4 v212, v[138:141], s[4:5]
	s_nop 1
	global_load_dwordx4 v[138:141], v212, s[82:83] offset:64
	s_waitcnt vmcnt(15)
	v_pk_add_f32 v[146:147], v[146:147], v[168:169] op_sel_hi:[1,0] neg_lo:[0,1] neg_hi:[0,1]
	v_pk_add_f32 v[148:149], v[148:149], v[168:169] op_sel_hi:[1,0] neg_lo:[0,1] neg_hi:[0,1]
	v_pk_mul_f32 v[146:147], v[146:147], v[168:169] op_sel:[0,1]
	v_pk_mul_f32 v[148:149], v[148:149], v[168:169] op_sel:[0,1]
	v_pk_fma_f32 v[146:147], v[190:191], v[146:147], v[194:195]
	v_pk_fma_f32 v[148:149], v[192:193], v[148:149], v[196:197]
	v_pk_fma_f32 v[146:147], v[106:107], v[186:187], v[146:147]
	v_pk_fma_f32 v[148:149], v[108:109], v[188:189], v[148:149]
	global_store_dwordx4 v213, v[146:149], s[4:5]
	s_nop 1
	global_load_dwordx4 v[146:149], v213, s[82:83] offset:64
	s_waitcnt vmcnt(16)
	v_pk_add_f32 v[150:151], v[150:151], v[170:171] op_sel_hi:[1,0] neg_lo:[0,1] neg_hi:[0,1]
	v_pk_add_f32 v[152:153], v[152:153], v[170:171] op_sel_hi:[1,0] neg_lo:[0,1] neg_hi:[0,1]
	v_pk_mul_f32 v[150:151], v[150:151], v[170:171] op_sel:[0,1]
	v_pk_mul_f32 v[152:153], v[152:153], v[170:171] op_sel:[0,1]
	v_pk_fma_f32 v[150:151], v[190:191], v[150:151], v[194:195]
	v_pk_fma_f32 v[152:153], v[192:193], v[152:153], v[196:197]
	v_pk_fma_f32 v[150:151], v[102:103], v[186:187], v[150:151]
	v_pk_fma_f32 v[152:153], v[104:105], v[188:189], v[152:153]
	global_store_dwordx4 v214, v[150:153], s[4:5]
	s_nop 1
	global_load_dwordx4 v[150:153], v214, s[82:83] offset:64
	s_waitcnt vmcnt(17)
	v_pk_add_f32 v[154:155], v[154:155], v[172:173] op_sel_hi:[1,0] neg_lo:[0,1] neg_hi:[0,1]
	v_pk_add_f32 v[156:157], v[156:157], v[172:173] op_sel_hi:[1,0] neg_lo:[0,1] neg_hi:[0,1]
	v_pk_mul_f32 v[154:155], v[154:155], v[172:173] op_sel:[0,1]
	v_pk_mul_f32 v[156:157], v[156:157], v[172:173] op_sel:[0,1]
	v_pk_fma_f32 v[154:155], v[190:191], v[154:155], v[194:195]
	v_pk_fma_f32 v[156:157], v[192:193], v[156:157], v[196:197]
	v_pk_fma_f32 v[154:155], v[98:99], v[186:187], v[154:155]
	v_pk_fma_f32 v[156:157], v[100:101], v[188:189], v[156:157]
	global_store_dwordx4 v215, v[154:157], s[4:5]
	s_nop 1
	global_load_dwordx4 v[154:157], v215, s[82:83] offset:64
	global_load_dwordx4 v[186:189], v216, s[6:7] offset:128
	global_load_dwordx4 v[190:193], v216, s[84:85] offset:128
	global_load_dwordx4 v[194:197], v216, s[86:87] offset:128
	s_waitcnt vmcnt(19)
	v_pk_mul_f32 v[202:203], v[202:203], s[70:71] op_sel_hi:[1,0]
	v_pk_mul_f32 v[204:205], v[204:205], s[70:71] op_sel_hi:[1,0]
	v_pk_mul_f32 v[206:207], v[206:207], s[70:71] op_sel_hi:[1,0]
	v_pk_mul_f32 v[208:209], v[208:209], s[70:71] op_sel_hi:[1,0]
	s_waitcnt vmcnt(17)
	v_pk_add_f32 v[114:115], v[114:115], v[126:127] op_sel_hi:[1,0] neg_lo:[0,1] neg_hi:[0,1]
	v_pk_add_f32 v[116:117], v[116:117], v[126:127] op_sel_hi:[1,0] neg_lo:[0,1] neg_hi:[0,1]
	v_pk_mul_f32 v[114:115], v[114:115], v[126:127] op_sel:[0,1]
	v_pk_mul_f32 v[116:117], v[116:117], v[126:127] op_sel:[0,1]
	v_pk_fma_f32 v[114:115], v[202:203], v[114:115], v[206:207]
	v_pk_fma_f32 v[116:117], v[204:205], v[116:117], v[208:209]
	v_pk_fma_f32 v[114:115], v[94:95], v[198:199], v[114:115]
	v_pk_fma_f32 v[116:117], v[96:97], v[200:201], v[116:117]
	global_store_dwordx4 v129, v[114:117], s[4:5] offset:64
	s_nop 1
	global_load_dwordx4 v[114:117], v129, s[82:83] offset:128
	s_waitcnt vmcnt(17)
	v_pk_add_f32 v[122:123], v[122:123], v[142:143] op_sel_hi:[1,0] neg_lo:[0,1] neg_hi:[0,1]
	v_pk_add_f32 v[124:125], v[124:125], v[142:143] op_sel_hi:[1,0] neg_lo:[0,1] neg_hi:[0,1]
	v_pk_mul_f32 v[122:123], v[122:123], v[142:143] op_sel:[0,1]
	v_pk_mul_f32 v[124:125], v[124:125], v[142:143] op_sel:[0,1]
	v_pk_fma_f32 v[122:123], v[202:203], v[122:123], v[206:207]
	v_pk_fma_f32 v[124:125], v[204:205], v[124:125], v[208:209]
	v_pk_fma_f32 v[122:123], v[90:91], v[198:199], v[122:123]
	v_pk_fma_f32 v[124:125], v[92:93], v[200:201], v[124:125]
	global_store_dwordx4 v145, v[122:125], s[4:5] offset:64
	s_nop 1
	global_load_dwordx4 v[122:125], v145, s[82:83] offset:128
	s_waitcnt vmcnt(17)
	v_pk_add_f32 v[130:131], v[130:131], v[158:159] op_sel_hi:[1,0] neg_lo:[0,1] neg_hi:[0,1]
	v_pk_add_f32 v[132:133], v[132:133], v[158:159] op_sel_hi:[1,0] neg_lo:[0,1] neg_hi:[0,1]
	v_pk_mul_f32 v[130:131], v[130:131], v[158:159] op_sel:[0,1]
	v_pk_mul_f32 v[132:133], v[132:133], v[158:159] op_sel:[0,1]
	v_pk_fma_f32 v[130:131], v[202:203], v[130:131], v[206:207]
	v_pk_fma_f32 v[132:133], v[204:205], v[132:133], v[208:209]
	v_pk_fma_f32 v[130:131], v[86:87], v[198:199], v[130:131]
	v_pk_fma_f32 v[132:133], v[88:89], v[200:201], v[132:133]
	global_store_dwordx4 v210, v[130:133], s[4:5] offset:64
	s_nop 1
	global_load_dwordx4 v[130:133], v210, s[82:83] offset:128
	s_waitcnt vmcnt(17)
	v_pk_add_f32 v[134:135], v[134:135], v[160:161] op_sel_hi:[1,0] neg_lo:[0,1] neg_hi:[0,1]
	v_pk_add_f32 v[136:137], v[136:137], v[160:161] op_sel_hi:[1,0] neg_lo:[0,1] neg_hi:[0,1]
	v_pk_mul_f32 v[134:135], v[134:135], v[160:161] op_sel:[0,1]
	v_pk_mul_f32 v[136:137], v[136:137], v[160:161] op_sel:[0,1]
	v_pk_fma_f32 v[134:135], v[202:203], v[134:135], v[206:207]
	v_pk_fma_f32 v[136:137], v[204:205], v[136:137], v[208:209]
	v_pk_fma_f32 v[134:135], v[82:83], v[198:199], v[134:135]
	v_pk_fma_f32 v[136:137], v[84:85], v[200:201], v[136:137]
	global_store_dwordx4 v211, v[134:137], s[4:5] offset:64
	s_nop 1
	global_load_dwordx4 v[134:137], v211, s[82:83] offset:128
	s_waitcnt vmcnt(17)
	v_pk_add_f32 v[138:139], v[138:139], v[166:167] op_sel_hi:[1,0] neg_lo:[0,1] neg_hi:[0,1]
	v_pk_add_f32 v[140:141], v[140:141], v[166:167] op_sel_hi:[1,0] neg_lo:[0,1] neg_hi:[0,1]
	v_pk_mul_f32 v[138:139], v[138:139], v[166:167] op_sel:[0,1]
	v_pk_mul_f32 v[140:141], v[140:141], v[166:167] op_sel:[0,1]
	v_pk_fma_f32 v[138:139], v[202:203], v[138:139], v[206:207]
	v_pk_fma_f32 v[140:141], v[204:205], v[140:141], v[208:209]
	v_pk_fma_f32 v[138:139], v[78:79], v[198:199], v[138:139]
	v_pk_fma_f32 v[140:141], v[80:81], v[200:201], v[140:141]
	global_store_dwordx4 v212, v[138:141], s[4:5] offset:64
	s_nop 1
	global_load_dwordx4 v[138:141], v212, s[82:83] offset:128
	s_waitcnt vmcnt(17)
	v_pk_add_f32 v[146:147], v[146:147], v[168:169] op_sel_hi:[1,0] neg_lo:[0,1] neg_hi:[0,1]
	v_pk_add_f32 v[148:149], v[148:149], v[168:169] op_sel_hi:[1,0] neg_lo:[0,1] neg_hi:[0,1]
	v_pk_mul_f32 v[146:147], v[146:147], v[168:169] op_sel:[0,1]
	v_pk_mul_f32 v[148:149], v[148:149], v[168:169] op_sel:[0,1]
	v_pk_fma_f32 v[146:147], v[202:203], v[146:147], v[206:207]
	v_pk_fma_f32 v[148:149], v[204:205], v[148:149], v[208:209]
	v_pk_fma_f32 v[146:147], v[74:75], v[198:199], v[146:147]
	v_pk_fma_f32 v[148:149], v[76:77], v[200:201], v[148:149]
	global_store_dwordx4 v213, v[146:149], s[4:5] offset:64
	s_nop 1
	global_load_dwordx4 v[146:149], v213, s[82:83] offset:128
	s_waitcnt vmcnt(17)
	v_pk_add_f32 v[150:151], v[150:151], v[170:171] op_sel_hi:[1,0] neg_lo:[0,1] neg_hi:[0,1]
	v_pk_add_f32 v[152:153], v[152:153], v[170:171] op_sel_hi:[1,0] neg_lo:[0,1] neg_hi:[0,1]
	v_pk_mul_f32 v[150:151], v[150:151], v[170:171] op_sel:[0,1]
	v_pk_mul_f32 v[152:153], v[152:153], v[170:171] op_sel:[0,1]
	v_pk_fma_f32 v[150:151], v[202:203], v[150:151], v[206:207]
	v_pk_fma_f32 v[152:153], v[204:205], v[152:153], v[208:209]
	v_pk_fma_f32 v[150:151], v[70:71], v[198:199], v[150:151]
	v_pk_fma_f32 v[152:153], v[72:73], v[200:201], v[152:153]
	global_store_dwordx4 v214, v[150:153], s[4:5] offset:64
	s_nop 1
	global_load_dwordx4 v[150:153], v214, s[82:83] offset:128
	s_waitcnt vmcnt(17)
	v_pk_add_f32 v[154:155], v[154:155], v[172:173] op_sel_hi:[1,0] neg_lo:[0,1] neg_hi:[0,1]
	v_pk_add_f32 v[156:157], v[156:157], v[172:173] op_sel_hi:[1,0] neg_lo:[0,1] neg_hi:[0,1]
	v_pk_mul_f32 v[154:155], v[154:155], v[172:173] op_sel:[0,1]
	v_pk_mul_f32 v[156:157], v[156:157], v[172:173] op_sel:[0,1]
	v_pk_fma_f32 v[154:155], v[202:203], v[154:155], v[206:207]
	v_pk_fma_f32 v[156:157], v[204:205], v[156:157], v[208:209]
	v_pk_fma_f32 v[154:155], v[66:67], v[198:199], v[154:155]
	v_pk_fma_f32 v[156:157], v[68:69], v[200:201], v[156:157]
	global_store_dwordx4 v215, v[154:157], s[4:5] offset:64
	s_nop 1
	global_load_dwordx4 v[154:157], v215, s[82:83] offset:128
	global_load_dwordx4 v[198:201], v216, s[6:7] offset:192
	global_load_dwordx4 v[202:205], v216, s[84:85] offset:192
	global_load_dwordx4 v[206:209], v216, s[86:87] offset:192
	s_waitcnt vmcnt(19)
	v_pk_mul_f32 v[190:191], v[190:191], s[70:71] op_sel_hi:[1,0]
	v_pk_mul_f32 v[192:193], v[192:193], s[70:71] op_sel_hi:[1,0]
	v_pk_mul_f32 v[194:195], v[194:195], s[70:71] op_sel_hi:[1,0]
	v_pk_mul_f32 v[196:197], v[196:197], s[70:71] op_sel_hi:[1,0]
	s_waitcnt vmcnt(17)
	v_pk_add_f32 v[114:115], v[114:115], v[126:127] op_sel_hi:[1,0] neg_lo:[0,1] neg_hi:[0,1]
	v_pk_add_f32 v[116:117], v[116:117], v[126:127] op_sel_hi:[1,0] neg_lo:[0,1] neg_hi:[0,1]
	v_pk_mul_f32 v[114:115], v[114:115], v[126:127] op_sel:[0,1]
	v_pk_mul_f32 v[116:117], v[116:117], v[126:127] op_sel:[0,1]
	v_pk_fma_f32 v[114:115], v[190:191], v[114:115], v[194:195]
	v_pk_fma_f32 v[116:117], v[192:193], v[116:117], v[196:197]
	v_pk_fma_f32 v[114:115], v[62:63], v[186:187], v[114:115]
	v_pk_fma_f32 v[116:117], v[64:65], v[188:189], v[116:117]
	global_store_dwordx4 v129, v[114:117], s[4:5] offset:128
	s_nop 1
	global_load_dwordx4 v[114:117], v129, s[82:83] offset:192
	s_waitcnt vmcnt(17)
	v_pk_add_f32 v[122:123], v[122:123], v[142:143] op_sel_hi:[1,0] neg_lo:[0,1] neg_hi:[0,1]
	v_pk_add_f32 v[124:125], v[124:125], v[142:143] op_sel_hi:[1,0] neg_lo:[0,1] neg_hi:[0,1]
	v_pk_mul_f32 v[122:123], v[122:123], v[142:143] op_sel:[0,1]
	v_pk_mul_f32 v[124:125], v[124:125], v[142:143] op_sel:[0,1]
	v_pk_fma_f32 v[122:123], v[190:191], v[122:123], v[194:195]
	v_pk_fma_f32 v[124:125], v[192:193], v[124:125], v[196:197]
	v_pk_fma_f32 v[122:123], v[58:59], v[186:187], v[122:123]
	v_pk_fma_f32 v[124:125], v[60:61], v[188:189], v[124:125]
	global_store_dwordx4 v145, v[122:125], s[4:5] offset:128
	s_nop 1
	global_load_dwordx4 v[122:125], v145, s[82:83] offset:192
	s_waitcnt vmcnt(17)
	v_pk_add_f32 v[130:131], v[130:131], v[158:159] op_sel_hi:[1,0] neg_lo:[0,1] neg_hi:[0,1]
	v_pk_add_f32 v[132:133], v[132:133], v[158:159] op_sel_hi:[1,0] neg_lo:[0,1] neg_hi:[0,1]
	v_pk_mul_f32 v[130:131], v[130:131], v[158:159] op_sel:[0,1]
	v_pk_mul_f32 v[132:133], v[132:133], v[158:159] op_sel:[0,1]
	v_pk_fma_f32 v[130:131], v[190:191], v[130:131], v[194:195]
	v_pk_fma_f32 v[132:133], v[192:193], v[132:133], v[196:197]
	v_pk_fma_f32 v[130:131], v[54:55], v[186:187], v[130:131]
	v_pk_fma_f32 v[132:133], v[56:57], v[188:189], v[132:133]
	global_store_dwordx4 v210, v[130:133], s[4:5] offset:128
	s_nop 1
	global_load_dwordx4 v[130:133], v210, s[82:83] offset:192
	s_waitcnt vmcnt(17)
	v_pk_add_f32 v[134:135], v[134:135], v[160:161] op_sel_hi:[1,0] neg_lo:[0,1] neg_hi:[0,1]
	v_pk_add_f32 v[136:137], v[136:137], v[160:161] op_sel_hi:[1,0] neg_lo:[0,1] neg_hi:[0,1]
	v_pk_mul_f32 v[134:135], v[134:135], v[160:161] op_sel:[0,1]
	v_pk_mul_f32 v[136:137], v[136:137], v[160:161] op_sel:[0,1]
	v_pk_fma_f32 v[134:135], v[190:191], v[134:135], v[194:195]
	v_pk_fma_f32 v[136:137], v[192:193], v[136:137], v[196:197]
	v_pk_fma_f32 v[134:135], v[50:51], v[186:187], v[134:135]
	v_pk_fma_f32 v[136:137], v[52:53], v[188:189], v[136:137]
	global_store_dwordx4 v211, v[134:137], s[4:5] offset:128
	s_nop 1
	global_load_dwordx4 v[134:137], v211, s[82:83] offset:192
	s_waitcnt vmcnt(17)
	v_pk_add_f32 v[138:139], v[138:139], v[166:167] op_sel_hi:[1,0] neg_lo:[0,1] neg_hi:[0,1]
	v_pk_add_f32 v[140:141], v[140:141], v[166:167] op_sel_hi:[1,0] neg_lo:[0,1] neg_hi:[0,1]
	v_pk_mul_f32 v[138:139], v[138:139], v[166:167] op_sel:[0,1]
	v_pk_mul_f32 v[140:141], v[140:141], v[166:167] op_sel:[0,1]
	v_pk_fma_f32 v[138:139], v[190:191], v[138:139], v[194:195]
	v_pk_fma_f32 v[140:141], v[192:193], v[140:141], v[196:197]
	v_pk_fma_f32 v[138:139], v[46:47], v[186:187], v[138:139]
	v_pk_fma_f32 v[140:141], v[48:49], v[188:189], v[140:141]
	global_store_dwordx4 v212, v[138:141], s[4:5] offset:128
	s_nop 1
	global_load_dwordx4 v[138:141], v212, s[82:83] offset:192
	s_waitcnt vmcnt(17)
	v_pk_add_f32 v[146:147], v[146:147], v[168:169] op_sel_hi:[1,0] neg_lo:[0,1] neg_hi:[0,1]
	v_pk_add_f32 v[148:149], v[148:149], v[168:169] op_sel_hi:[1,0] neg_lo:[0,1] neg_hi:[0,1]
	v_pk_mul_f32 v[146:147], v[146:147], v[168:169] op_sel:[0,1]
	v_pk_mul_f32 v[148:149], v[148:149], v[168:169] op_sel:[0,1]
	v_pk_fma_f32 v[146:147], v[190:191], v[146:147], v[194:195]
	v_pk_fma_f32 v[148:149], v[192:193], v[148:149], v[196:197]
	v_pk_fma_f32 v[146:147], v[42:43], v[186:187], v[146:147]
	v_pk_fma_f32 v[148:149], v[44:45], v[188:189], v[148:149]
	global_store_dwordx4 v213, v[146:149], s[4:5] offset:128
	s_nop 1
	global_load_dwordx4 v[146:149], v213, s[82:83] offset:192
	s_waitcnt vmcnt(17)
	v_pk_add_f32 v[150:151], v[150:151], v[170:171] op_sel_hi:[1,0] neg_lo:[0,1] neg_hi:[0,1]
	v_pk_add_f32 v[152:153], v[152:153], v[170:171] op_sel_hi:[1,0] neg_lo:[0,1] neg_hi:[0,1]
	v_pk_mul_f32 v[150:151], v[150:151], v[170:171] op_sel:[0,1]
	v_pk_mul_f32 v[152:153], v[152:153], v[170:171] op_sel:[0,1]
	v_pk_fma_f32 v[150:151], v[190:191], v[150:151], v[194:195]
	v_pk_fma_f32 v[152:153], v[192:193], v[152:153], v[196:197]
	v_pk_fma_f32 v[150:151], v[38:39], v[186:187], v[150:151]
	v_pk_fma_f32 v[152:153], v[40:41], v[188:189], v[152:153]
	global_store_dwordx4 v214, v[150:153], s[4:5] offset:128
	s_nop 1
	global_load_dwordx4 v[150:153], v214, s[82:83] offset:192
	s_waitcnt vmcnt(17)
	v_pk_add_f32 v[154:155], v[154:155], v[172:173] op_sel_hi:[1,0] neg_lo:[0,1] neg_hi:[0,1]
	v_pk_add_f32 v[156:157], v[156:157], v[172:173] op_sel_hi:[1,0] neg_lo:[0,1] neg_hi:[0,1]
	v_pk_mul_f32 v[154:155], v[154:155], v[172:173] op_sel:[0,1]
	v_pk_mul_f32 v[156:157], v[156:157], v[172:173] op_sel:[0,1]
	v_pk_fma_f32 v[154:155], v[190:191], v[154:155], v[194:195]
	v_pk_fma_f32 v[156:157], v[192:193], v[156:157], v[196:197]
	v_pk_fma_f32 v[154:155], v[34:35], v[186:187], v[154:155]
	v_pk_fma_f32 v[156:157], v[36:37], v[188:189], v[156:157]
	global_store_dwordx4 v215, v[154:157], s[4:5] offset:128
	s_nop 1
	global_load_dwordx4 v[154:157], v215, s[82:83] offset:192
	s_waitcnt vmcnt(16)
	v_pk_mul_f32 v[202:203], v[202:203], s[70:71] op_sel_hi:[1,0]
	v_pk_mul_f32 v[204:205], v[204:205], s[70:71] op_sel_hi:[1,0]
	v_pk_mul_f32 v[206:207], v[206:207], s[70:71] op_sel_hi:[1,0]
	v_pk_mul_f32 v[208:209], v[208:209], s[70:71] op_sel_hi:[1,0]
	s_waitcnt vmcnt(14)
	v_pk_add_f32 v[114:115], v[114:115], v[126:127] op_sel_hi:[1,0] neg_lo:[0,1] neg_hi:[0,1]
	v_pk_add_f32 v[116:117], v[116:117], v[126:127] op_sel_hi:[1,0] neg_lo:[0,1] neg_hi:[0,1]
	v_pk_mul_f32 v[114:115], v[114:115], v[126:127] op_sel:[0,1]
	v_pk_mul_f32 v[116:117], v[116:117], v[126:127] op_sel:[0,1]
	v_pk_fma_f32 v[114:115], v[202:203], v[114:115], v[206:207]
	v_pk_fma_f32 v[116:117], v[204:205], v[116:117], v[208:209]
	v_pk_fma_f32 v[114:115], v[30:31], v[198:199], v[114:115]
	v_pk_fma_f32 v[116:117], v[32:33], v[200:201], v[116:117]
	global_store_dwordx4 v129, v[114:117], s[4:5] offset:192
	s_waitcnt vmcnt(13)
	v_pk_add_f32 v[122:123], v[122:123], v[142:143] op_sel_hi:[1,0] neg_lo:[0,1] neg_hi:[0,1]
	v_pk_add_f32 v[124:125], v[124:125], v[142:143] op_sel_hi:[1,0] neg_lo:[0,1] neg_hi:[0,1]
	v_pk_mul_f32 v[122:123], v[122:123], v[142:143] op_sel:[0,1]
	v_pk_mul_f32 v[124:125], v[124:125], v[142:143] op_sel:[0,1]
	v_pk_fma_f32 v[122:123], v[202:203], v[122:123], v[206:207]
	v_pk_fma_f32 v[124:125], v[204:205], v[124:125], v[208:209]
	v_pk_fma_f32 v[122:123], v[26:27], v[198:199], v[122:123]
	v_pk_fma_f32 v[124:125], v[28:29], v[200:201], v[124:125]
	global_store_dwordx4 v145, v[122:125], s[4:5] offset:192
	s_waitcnt vmcnt(12)
	v_pk_add_f32 v[130:131], v[130:131], v[158:159] op_sel_hi:[1,0] neg_lo:[0,1] neg_hi:[0,1]
	v_pk_add_f32 v[132:133], v[132:133], v[158:159] op_sel_hi:[1,0] neg_lo:[0,1] neg_hi:[0,1]
	v_pk_mul_f32 v[130:131], v[130:131], v[158:159] op_sel:[0,1]
	v_pk_mul_f32 v[132:133], v[132:133], v[158:159] op_sel:[0,1]
	v_pk_fma_f32 v[130:131], v[202:203], v[130:131], v[206:207]
	v_pk_fma_f32 v[132:133], v[204:205], v[132:133], v[208:209]
	v_pk_fma_f32 v[130:131], v[22:23], v[198:199], v[130:131]
	v_pk_fma_f32 v[132:133], v[24:25], v[200:201], v[132:133]
	global_store_dwordx4 v210, v[130:133], s[4:5] offset:192
	s_waitcnt vmcnt(11)
	v_pk_add_f32 v[134:135], v[134:135], v[160:161] op_sel_hi:[1,0] neg_lo:[0,1] neg_hi:[0,1]
	v_pk_add_f32 v[136:137], v[136:137], v[160:161] op_sel_hi:[1,0] neg_lo:[0,1] neg_hi:[0,1]
	v_pk_mul_f32 v[134:135], v[134:135], v[160:161] op_sel:[0,1]
	v_pk_mul_f32 v[136:137], v[136:137], v[160:161] op_sel:[0,1]
	v_pk_fma_f32 v[134:135], v[202:203], v[134:135], v[206:207]
	v_pk_fma_f32 v[136:137], v[204:205], v[136:137], v[208:209]
	v_pk_fma_f32 v[134:135], v[18:19], v[198:199], v[134:135]
	v_pk_fma_f32 v[136:137], v[20:21], v[200:201], v[136:137]
	global_store_dwordx4 v211, v[134:137], s[4:5] offset:192
	s_waitcnt vmcnt(10)
	v_pk_add_f32 v[138:139], v[138:139], v[166:167] op_sel_hi:[1,0] neg_lo:[0,1] neg_hi:[0,1]
	v_pk_add_f32 v[140:141], v[140:141], v[166:167] op_sel_hi:[1,0] neg_lo:[0,1] neg_hi:[0,1]
	v_pk_mul_f32 v[138:139], v[138:139], v[166:167] op_sel:[0,1]
	v_pk_mul_f32 v[140:141], v[140:141], v[166:167] op_sel:[0,1]
	v_pk_fma_f32 v[138:139], v[202:203], v[138:139], v[206:207]
	v_pk_fma_f32 v[140:141], v[204:205], v[140:141], v[208:209]
	v_pk_fma_f32 v[138:139], v[14:15], v[198:199], v[138:139]
	v_pk_fma_f32 v[140:141], v[16:17], v[200:201], v[140:141]
	global_store_dwordx4 v212, v[138:141], s[4:5] offset:192
	s_waitcnt vmcnt(9)
	v_pk_add_f32 v[146:147], v[146:147], v[168:169] op_sel_hi:[1,0] neg_lo:[0,1] neg_hi:[0,1]
	v_pk_add_f32 v[148:149], v[148:149], v[168:169] op_sel_hi:[1,0] neg_lo:[0,1] neg_hi:[0,1]
	v_pk_mul_f32 v[146:147], v[146:147], v[168:169] op_sel:[0,1]
	v_pk_mul_f32 v[148:149], v[148:149], v[168:169] op_sel:[0,1]
	v_pk_fma_f32 v[146:147], v[202:203], v[146:147], v[206:207]
	v_pk_fma_f32 v[148:149], v[204:205], v[148:149], v[208:209]
	v_pk_fma_f32 v[146:147], v[10:11], v[198:199], v[146:147]
	v_pk_fma_f32 v[148:149], v[12:13], v[200:201], v[148:149]
	global_store_dwordx4 v213, v[146:149], s[4:5] offset:192
	s_waitcnt vmcnt(8)
	v_pk_add_f32 v[150:151], v[150:151], v[170:171] op_sel_hi:[1,0] neg_lo:[0,1] neg_hi:[0,1]
	v_pk_add_f32 v[152:153], v[152:153], v[170:171] op_sel_hi:[1,0] neg_lo:[0,1] neg_hi:[0,1]
	v_pk_mul_f32 v[150:151], v[150:151], v[170:171] op_sel:[0,1]
	v_pk_mul_f32 v[152:153], v[152:153], v[170:171] op_sel:[0,1]
	v_pk_fma_f32 v[150:151], v[202:203], v[150:151], v[206:207]
	v_pk_fma_f32 v[152:153], v[204:205], v[152:153], v[208:209]
	v_pk_fma_f32 v[150:151], v[6:7], v[198:199], v[150:151]
	v_pk_fma_f32 v[152:153], v[8:9], v[200:201], v[152:153]
	global_store_dwordx4 v214, v[150:153], s[4:5] offset:192
	s_waitcnt vmcnt(7)
	v_pk_add_f32 v[154:155], v[154:155], v[172:173] op_sel_hi:[1,0] neg_lo:[0,1] neg_hi:[0,1]
	v_pk_add_f32 v[156:157], v[156:157], v[172:173] op_sel_hi:[1,0] neg_lo:[0,1] neg_hi:[0,1]
	v_pk_mul_f32 v[154:155], v[154:155], v[172:173] op_sel:[0,1]
	v_pk_mul_f32 v[156:157], v[156:157], v[172:173] op_sel:[0,1]
	v_pk_fma_f32 v[154:155], v[202:203], v[154:155], v[206:207]
	v_pk_fma_f32 v[156:157], v[204:205], v[156:157], v[208:209]
	v_pk_fma_f32 v[154:155], v[2:3], v[198:199], v[154:155]
	v_pk_fma_f32 v[156:157], v[4:5], v[200:201], v[156:157]
	global_store_dwordx4 v215, v[154:157], s[4:5] offset:192
	s_add_i32 s61, s61, s30
	s_cmpk_gt_i32 s61, 0xff
	s_cbranch_scc1 .LBB0_839

.LBB0_1029:
	s_add_i32 s5, s36, 0x400
	s_lshl_b32 s4, s72, 8
	v_lshrrev_b32_e32 v0, 4, v139
	v_add3_u32 v134, s5, v142, v141
	v_add3_u32 v135, s39, v143, v141
	s_setprio 3
	ds_read_b128 v[130:133], v135
	ds_read_b128 v[140:143], v135 offset:2048
	ds_read_b128 v[144:147], v135 offset:4096
	ds_read_b128 v[148:151], v135 offset:6144
	ds_read_b128 v[152:155], v134
	ds_read_b128 v[156:159], v134 offset:2048
	ds_read_b128 v[166:169], v134 offset:4096
	ds_read_b128 v[170:173], v134 offset:6144
	ds_read_b128 v[174:177], v134 offset:8192
	s_waitcnt lgkmcnt(4)
	v_mfma_f32_16x16x32_bf16 v[126:129], v[130:133], v[152:155], v[126:129]
	v_mfma_f32_16x16x32_bf16 v[122:125], v[140:143], v[152:155], v[122:125]
	v_mfma_f32_16x16x32_bf16 v[118:121], v[144:147], v[152:155], v[118:121]
	v_mfma_f32_16x16x32_bf16 v[114:117], v[148:151], v[152:155], v[114:117]
	ds_read_b128 v[152:155], v134 offset:10240
	s_waitcnt lgkmcnt(4)
	v_mfma_f32_16x16x32_bf16 v[110:113], v[130:133], v[156:159], v[110:113]
	v_mfma_f32_16x16x32_bf16 v[106:109], v[140:143], v[156:159], v[106:109]
	v_mfma_f32_16x16x32_bf16 v[102:105], v[144:147], v[156:159], v[102:105]
	v_mfma_f32_16x16x32_bf16 v[98:101], v[148:151], v[156:159], v[98:101]
	ds_read_b128 v[156:159], v134 offset:12288
	s_waitcnt lgkmcnt(4)
	v_mfma_f32_16x16x32_bf16 v[186:189], v[130:133], v[166:169], v[94:97]
	v_mfma_f32_16x16x32_bf16 v[190:193], v[140:143], v[166:169], v[90:93]
	v_mfma_f32_16x16x32_bf16 v[194:197], v[144:147], v[166:169], v[86:89]
	v_mfma_f32_16x16x32_bf16 v[82:85], v[148:151], v[166:169], v[82:85]
	s_nop 1
	ds_read_b128 v[86:89], v134 offset:14336
	s_waitcnt lgkmcnt(4)
	v_mfma_f32_16x16x32_bf16 v[78:81], v[130:133], v[170:173], v[78:81]
	v_mfma_f32_16x16x32_bf16 v[74:77], v[140:143], v[170:173], v[74:77]
	v_mfma_f32_16x16x32_bf16 v[70:73], v[144:147], v[170:173], v[70:73]
	v_mfma_f32_16x16x32_bf16 v[66:69], v[148:151], v[170:173], v[66:69]
	s_waitcnt lgkmcnt(3)
	v_mfma_f32_16x16x32_bf16 v[166:169], v[130:133], v[174:177], v[62:65]
	v_mfma_f32_16x16x32_bf16 v[170:173], v[140:143], v[174:177], v[58:61]
	v_mfma_f32_16x16x32_bf16 v[198:201], v[144:147], v[174:177], v[54:57]
	v_mfma_f32_16x16x32_bf16 v[174:177], v[148:151], v[174:177], v[50:53]
	s_waitcnt lgkmcnt(2)
	v_mfma_f32_16x16x32_bf16 v[202:205], v[130:133], v[152:155], v[46:49]
	v_mfma_f32_16x16x32_bf16 v[42:45], v[140:143], v[152:155], v[42:45]
	v_mfma_f32_16x16x32_bf16 v[38:41], v[144:147], v[152:155], v[38:41]
	v_mfma_f32_16x16x32_bf16 v[34:37], v[148:151], v[152:155], v[34:37]
	s_waitcnt lgkmcnt(1)
	v_mfma_f32_16x16x32_bf16 v[152:155], v[130:133], v[156:159], v[30:33]
	v_mfma_f32_16x16x32_bf16 v[206:209], v[140:143], v[156:159], v[26:29]
	v_mfma_f32_16x16x32_bf16 v[210:213], v[144:147], v[156:159], v[22:25]
	v_mfma_f32_16x16x32_bf16 v[156:159], v[148:151], v[156:159], v[18:21]
	s_waitcnt lgkmcnt(0)
	v_mfma_f32_16x16x32_bf16 v[130:133], v[130:133], v[86:89], v[14:17]
	v_mfma_f32_16x16x32_bf16 v[140:143], v[140:143], v[86:89], v[10:13]
	v_mfma_f32_16x16x32_bf16 v[144:147], v[144:147], v[86:89], v[6:9]
	v_mfma_f32_16x16x32_bf16 v[2:5], v[148:151], v[86:89], v[2:5]
	s_setprio 0
	s_setprio 3
	ds_read_b128 v[148:151], v135 offset:1024
	ds_read_b128 v[214:217], v135 offset:3072
	ds_read_b128 v[218:221], v135 offset:5120
	ds_read_b128 v[222:225], v135 offset:7168
	ds_read_b128 v[6:9], v134 offset:1024
	ds_read_b128 v[10:13], v134 offset:3072
	ds_read_b128 v[14:17], v134 offset:5120
	ds_read_b128 v[18:21], v134 offset:7168
	ds_read_b128 v[226:229], v134 offset:9216
	s_waitcnt lgkmcnt(4)
	v_mfma_f32_16x16x32_bf16 v[230:233], v[148:151], v[6:9], v[126:129]
	v_mfma_f32_16x16x32_bf16 v[94:97], v[214:217], v[6:9], v[122:125]
	v_mfma_f32_16x16x32_bf16 v[62:65], v[218:221], v[6:9], v[118:121]
	v_mfma_f32_16x16x32_bf16 v[30:33], v[222:225], v[6:9], v[114:117]
	ds_read_b128 v[6:9], v134 offset:11264
	s_waitcnt lgkmcnt(4)
	v_mfma_f32_16x16x32_bf16 v[234:237], v[148:151], v[10:13], v[110:113]
	v_mfma_f32_16x16x32_bf16 v[90:93], v[214:217], v[10:13], v[106:109]
	v_mfma_f32_16x16x32_bf16 v[58:61], v[218:221], v[10:13], v[102:105]
	v_mfma_f32_16x16x32_bf16 v[26:29], v[222:225], v[10:13], v[98:101]
	s_nop 2
	ds_read_b128 v[98:101], v134 offset:13312
	s_waitcnt lgkmcnt(4)
	v_mfma_f32_16x16x32_bf16 v[122:125], v[148:151], v[14:17], v[186:189]
	v_mfma_f32_16x16x32_bf16 v[86:89], v[214:217], v[14:17], v[190:193]
	v_mfma_f32_16x16x32_bf16 v[54:57], v[218:221], v[14:17], v[194:197]
	v_mfma_f32_16x16x32_bf16 v[22:25], v[222:225], v[14:17], v[82:85]
	ds_read_b128 v[110:113], v134 offset:15360
	s_waitcnt lgkmcnt(4)
	v_mfma_f32_16x16x32_bf16 v[118:121], v[148:151], v[18:21], v[78:81]
	v_mfma_f32_16x16x32_bf16 v[82:85], v[214:217], v[18:21], v[74:77]
	v_mfma_f32_16x16x32_bf16 v[50:53], v[218:221], v[18:21], v[70:73]
	v_mfma_f32_16x16x32_bf16 v[18:21], v[222:225], v[18:21], v[66:69]
	s_waitcnt lgkmcnt(3)
	v_mfma_f32_16x16x32_bf16 v[114:117], v[148:151], v[226:229], v[166:169]
	v_mfma_f32_16x16x32_bf16 v[78:81], v[214:217], v[226:229], v[170:173]
	v_mfma_f32_16x16x32_bf16 v[46:49], v[218:221], v[226:229], v[198:201]
	v_mfma_f32_16x16x32_bf16 v[14:17], v[222:225], v[226:229], v[174:177]
	s_waitcnt lgkmcnt(2)
	v_mfma_f32_16x16x32_bf16 v[106:109], v[148:151], v[6:9], v[202:205]
	v_mfma_f32_16x16x32_bf16 v[74:77], v[214:217], v[6:9], v[42:45]
	v_mfma_f32_16x16x32_bf16 v[42:45], v[218:221], v[6:9], v[38:41]
	v_mfma_f32_16x16x32_bf16 v[10:13], v[222:225], v[6:9], v[34:37]
	s_waitcnt lgkmcnt(1)
	v_mfma_f32_16x16x32_bf16 v[102:105], v[148:151], v[98:101], v[152:155]
	v_mfma_f32_16x16x32_bf16 v[70:73], v[214:217], v[98:101], v[206:209]
	v_mfma_f32_16x16x32_bf16 v[38:41], v[218:221], v[98:101], v[210:213]
	v_mfma_f32_16x16x32_bf16 v[6:9], v[222:225], v[98:101], v[156:159]
	s_waitcnt lgkmcnt(0)
	v_mfma_f32_16x16x32_bf16 v[98:101], v[148:151], v[110:113], v[130:133]
	v_mfma_f32_16x16x32_bf16 v[66:69], v[214:217], v[110:113], v[140:143]
	v_mfma_f32_16x16x32_bf16 v[34:37], v[218:221], v[110:113], v[144:147]
	v_mfma_f32_16x16x32_bf16 v[2:5], v[222:225], v[110:113], v[2:5]
	s_setprio 0
	v_lshlrev_b32_e32 v111, 7, v136
	s_waitcnt vmcnt(0)
	s_barrier
	v_lshl_or_b32 v110, v138, 6, s4
	v_add3_u32 v144, v111, s61, v137
	v_lshl_add_u32 v132, v0, 2, v110
	v_lshlrev_b32_e32 v133, 12, v144
	v_lshl_add_u32 v133, v132, 2, v133
	v_add_u32_e32 v145, 0x10000, v133
	v_add_u32_e32 v210, 0x20000, v133
	v_add_u32_e32 v211, 0x30000, v133
	v_add_u32_e32 v212, 0x40000, v133
	v_add_u32_e32 v213, 0x50000, v133
	v_add_u32_e32 v214, 0x60000, v133
	v_add_u32_e32 v215, 0x70000, v133
	v_lshlrev_b32_e32 v216, 2, v132
	v_lshlrev_b32_e32 v217, 3, v144
	global_load_dwordx2 v[130:131], v217, s[86:87]
	global_load_dwordx2 v[142:143], v217, s[86:87] offset:128
	global_load_dwordx2 v[166:167], v217, s[86:87] offset:256
	global_load_dwordx2 v[168:169], v217, s[86:87] offset:384
	global_load_dwordx2 v[170:171], v217, s[86:87] offset:512
	global_load_dwordx2 v[172:173], v217, s[86:87] offset:640
	global_load_dwordx2 v[174:175], v217, s[86:87] offset:768
	global_load_dwordx2 v[176:177], v217, s[86:87] offset:896
	global_load_dwordx4 v[186:189], v216, s[84:85]
	global_load_dwordx4 v[190:193], v216, s[10:11]
	global_load_dwordx4 v[194:197], v216, s[80:81]
	global_load_dwordx4 v[110:113], v133, s[82:83]
	global_load_dwordx4 v[126:129], v145, s[82:83]
	global_load_dwordx4 v[134:137], v210, s[82:83]
	global_load_dwordx4 v[138:141], v211, s[82:83]
	global_load_dwordx4 v[146:149], v212, s[82:83]
	global_load_dwordx4 v[150:153], v213, s[82:83]
	global_load_dwordx4 v[154:157], v214, s[82:83]
	global_load_dwordx4 v[158:161], v215, s[82:83]
	global_load_dwordx4 v[198:201], v216, s[84:85] offset:64
	global_load_dwordx4 v[202:205], v216, s[10:11] offset:64
	global_load_dwordx4 v[206:209], v216, s[80:81] offset:64
	s_waitcnt vmcnt(11)
	v_pk_mul_f32 v[190:191], v[190:191], s[70:71] op_sel_hi:[1,0]
	v_pk_mul_f32 v[192:193], v[192:193], s[70:71] op_sel_hi:[1,0]
	v_pk_mul_f32 v[194:195], v[194:195], s[70:71] op_sel_hi:[1,0]
	v_pk_mul_f32 v[196:197], v[196:197], s[70:71] op_sel_hi:[1,0]
	s_waitcnt vmcnt(10)
	v_pk_add_f32 v[110:111], v[110:111], v[130:131] op_sel_hi:[1,0] neg_lo:[0,1] neg_hi:[0,1]
	v_pk_add_f32 v[112:113], v[112:113], v[130:131] op_sel_hi:[1,0] neg_lo:[0,1] neg_hi:[0,1]
	v_pk_mul_f32 v[110:111], v[110:111], v[130:131] op_sel:[0,1]
	v_pk_mul_f32 v[112:113], v[112:113], v[130:131] op_sel:[0,1]
	v_pk_fma_f32 v[110:111], v[190:191], v[110:111], v[194:195]
	v_pk_fma_f32 v[112:113], v[192:193], v[112:113], v[196:197]
	v_pk_fma_f32 v[110:111], v[230:231], v[186:187], v[110:111]
	v_pk_fma_f32 v[112:113], v[232:233], v[188:189], v[112:113]
	global_store_dwordx4 v133, v[110:113], s[82:83]
	s_nop 1
	global_load_dwordx4 v[110:113], v133, s[82:83] offset:64
	s_waitcnt vmcnt(11)
	v_pk_add_f32 v[126:127], v[126:127], v[142:143] op_sel_hi:[1,0] neg_lo:[0,1] neg_hi:[0,1]
	v_pk_add_f32 v[128:129], v[128:129], v[142:143] op_sel_hi:[1,0] neg_lo:[0,1] neg_hi:[0,1]
	v_pk_mul_f32 v[126:127], v[126:127], v[142:143] op_sel:[0,1]
	v_pk_mul_f32 v[128:129], v[128:129], v[142:143] op_sel:[0,1]
	v_pk_fma_f32 v[126:127], v[190:191], v[126:127], v[194:195]
	v_pk_fma_f32 v[128:129], v[192:193], v[128:129], v[196:197]
	v_pk_fma_f32 v[126:127], v[234:235], v[186:187], v[126:127]
	v_pk_fma_f32 v[128:129], v[236:237], v[188:189], v[128:129]
	global_store_dwordx4 v145, v[126:129], s[82:83]
	s_nop 1
	global_load_dwordx4 v[126:129], v145, s[82:83] offset:64
	s_waitcnt vmcnt(12)
	v_pk_add_f32 v[134:135], v[134:135], v[166:167] op_sel_hi:[1,0] neg_lo:[0,1] neg_hi:[0,1]
	v_pk_add_f32 v[136:137], v[136:137], v[166:167] op_sel_hi:[1,0] neg_lo:[0,1] neg_hi:[0,1]
	v_pk_mul_f32 v[134:135], v[134:135], v[166:167] op_sel:[0,1]
	v_pk_mul_f32 v[136:137], v[136:137], v[166:167] op_sel:[0,1]
	v_pk_fma_f32 v[134:135], v[190:191], v[134:135], v[194:195]
	v_pk_fma_f32 v[136:137], v[192:193], v[136:137], v[196:197]
	v_pk_fma_f32 v[134:135], v[122:123], v[186:187], v[134:135]
	v_pk_fma_f32 v[136:137], v[124:125], v[188:189], v[136:137]
	global_store_dwordx4 v210, v[134:137], s[82:83]
	s_nop 1
	global_load_dwordx4 v[134:137], v210, s[82:83] offset:64
	s_waitcnt vmcnt(13)
	v_pk_add_f32 v[138:139], v[138:139], v[168:169] op_sel_hi:[1,0] neg_lo:[0,1] neg_hi:[0,1]
	v_pk_add_f32 v[140:141], v[140:141], v[168:169] op_sel_hi:[1,0] neg_lo:[0,1] neg_hi:[0,1]
	v_pk_mul_f32 v[138:139], v[138:139], v[168:169] op_sel:[0,1]
	v_pk_mul_f32 v[140:141], v[140:141], v[168:169] op_sel:[0,1]
	v_pk_fma_f32 v[138:139], v[190:191], v[138:139], v[194:195]
	v_pk_fma_f32 v[140:141], v[192:193], v[140:141], v[196:197]
	v_pk_fma_f32 v[138:139], v[118:119], v[186:187], v[138:139]
	v_pk_fma_f32 v[140:141], v[120:121], v[188:189], v[140:141]
	global_store_dwordx4 v211, v[138:141], s[82:83]
	s_nop 1
	global_load_dwordx4 v[138:141], v211, s[82:83] offset:64
	s_waitcnt vmcnt(14)
	v_pk_add_f32 v[146:147], v[146:147], v[170:171] op_sel_hi:[1,0] neg_lo:[0,1] neg_hi:[0,1]
	v_pk_add_f32 v[148:149], v[148:149], v[170:171] op_sel_hi:[1,0] neg_lo:[0,1] neg_hi:[0,1]
	v_pk_mul_f32 v[146:147], v[146:147], v[170:171] op_sel:[0,1]
	v_pk_mul_f32 v[148:149], v[148:149], v[170:171] op_sel:[0,1]
	v_pk_fma_f32 v[146:147], v[190:191], v[146:147], v[194:195]
	v_pk_fma_f32 v[148:149], v[192:193], v[148:149], v[196:197]
	v_pk_fma_f32 v[146:147], v[114:115], v[186:187], v[146:147]
	v_pk_fma_f32 v[148:149], v[116:117], v[188:189], v[148:149]
	global_store_dwordx4 v212, v[146:149], s[82:83]
	s_nop 1
	global_load_dwordx4 v[146:149], v212, s[82:83] offset:64
	s_waitcnt vmcnt(15)
	v_pk_add_f32 v[150:151], v[150:151], v[172:173] op_sel_hi:[1,0] neg_lo:[0,1] neg_hi:[0,1]
	v_pk_add_f32 v[152:153], v[152:153], v[172:173] op_sel_hi:[1,0] neg_lo:[0,1] neg_hi:[0,1]
	v_pk_mul_f32 v[150:151], v[150:151], v[172:173] op_sel:[0,1]
	v_pk_mul_f32 v[152:153], v[152:153], v[172:173] op_sel:[0,1]
	v_pk_fma_f32 v[150:151], v[190:191], v[150:151], v[194:195]
	v_pk_fma_f32 v[152:153], v[192:193], v[152:153], v[196:197]
	v_pk_fma_f32 v[150:151], v[106:107], v[186:187], v[150:151]
	v_pk_fma_f32 v[152:153], v[108:109], v[188:189], v[152:153]
	global_store_dwordx4 v213, v[150:153], s[82:83]
	s_nop 1
	global_load_dwordx4 v[150:153], v213, s[82:83] offset:64
	s_waitcnt vmcnt(16)
	v_pk_add_f32 v[154:155], v[154:155], v[174:175] op_sel_hi:[1,0] neg_lo:[0,1] neg_hi:[0,1]
	v_pk_add_f32 v[156:157], v[156:157], v[174:175] op_sel_hi:[1,0] neg_lo:[0,1] neg_hi:[0,1]
	v_pk_mul_f32 v[154:155], v[154:155], v[174:175] op_sel:[0,1]
	v_pk_mul_f32 v[156:157], v[156:157], v[174:175] op_sel:[0,1]
	v_pk_fma_f32 v[154:155], v[190:191], v[154:155], v[194:195]
	v_pk_fma_f32 v[156:157], v[192:193], v[156:157], v[196:197]
	v_pk_fma_f32 v[154:155], v[102:103], v[186:187], v[154:155]
	v_pk_fma_f32 v[156:157], v[104:105], v[188:189], v[156:157]
	global_store_dwordx4 v214, v[154:157], s[82:83]
	s_nop 1
	global_load_dwordx4 v[154:157], v214, s[82:83] offset:64
	s_waitcnt vmcnt(17)
	v_pk_add_f32 v[158:159], v[158:159], v[176:177] op_sel_hi:[1,0] neg_lo:[0,1] neg_hi:[0,1]
	v_pk_add_f32 v[160:161], v[160:161], v[176:177] op_sel_hi:[1,0] neg_lo:[0,1] neg_hi:[0,1]
	v_pk_mul_f32 v[158:159], v[158:159], v[176:177] op_sel:[0,1]
	v_pk_mul_f32 v[160:161], v[160:161], v[176:177] op_sel:[0,1]
	v_pk_fma_f32 v[158:159], v[190:191], v[158:159], v[194:195]
	v_pk_fma_f32 v[160:161], v[192:193], v[160:161], v[196:197]
	v_pk_fma_f32 v[158:159], v[98:99], v[186:187], v[158:159]
	v_pk_fma_f32 v[160:161], v[100:101], v[188:189], v[160:161]
	global_store_dwordx4 v215, v[158:161], s[82:83]
	s_nop 1
	global_load_dwordx4 v[158:161], v215, s[82:83] offset:64
	global_load_dwordx4 v[186:189], v216, s[84:85] offset:128
	global_load_dwordx4 v[190:193], v216, s[10:11] offset:128
	global_load_dwordx4 v[194:197], v216, s[80:81] offset:128
	s_waitcnt vmcnt(19)
	v_pk_mul_f32 v[202:203], v[202:203], s[70:71] op_sel_hi:[1,0]
	v_pk_mul_f32 v[204:205], v[204:205], s[70:71] op_sel_hi:[1,0]
	v_pk_mul_f32 v[206:207], v[206:207], s[70:71] op_sel_hi:[1,0]
	v_pk_mul_f32 v[208:209], v[208:209], s[70:71] op_sel_hi:[1,0]
	s_waitcnt vmcnt(17)
	v_pk_add_f32 v[110:111], v[110:111], v[130:131] op_sel_hi:[1,0] neg_lo:[0,1] neg_hi:[0,1]
	v_pk_add_f32 v[112:113], v[112:113], v[130:131] op_sel_hi:[1,0] neg_lo:[0,1] neg_hi:[0,1]
	v_pk_mul_f32 v[110:111], v[110:111], v[130:131] op_sel:[0,1]
	v_pk_mul_f32 v[112:113], v[112:113], v[130:131] op_sel:[0,1]
	v_pk_fma_f32 v[110:111], v[202:203], v[110:111], v[206:207]
	v_pk_fma_f32 v[112:113], v[204:205], v[112:113], v[208:209]
	v_pk_fma_f32 v[110:111], v[94:95], v[198:199], v[110:111]
	v_pk_fma_f32 v[112:113], v[96:97], v[200:201], v[112:113]
	global_store_dwordx4 v133, v[110:113], s[82:83] offset:64
	s_nop 1
	global_load_dwordx4 v[110:113], v133, s[82:83] offset:128
	s_waitcnt vmcnt(17)
	v_pk_add_f32 v[126:127], v[126:127], v[142:143] op_sel_hi:[1,0] neg_lo:[0,1] neg_hi:[0,1]
	v_pk_add_f32 v[128:129], v[128:129], v[142:143] op_sel_hi:[1,0] neg_lo:[0,1] neg_hi:[0,1]
	v_pk_mul_f32 v[126:127], v[126:127], v[142:143] op_sel:[0,1]
	v_pk_mul_f32 v[128:129], v[128:129], v[142:143] op_sel:[0,1]
	v_pk_fma_f32 v[126:127], v[202:203], v[126:127], v[206:207]
	v_pk_fma_f32 v[128:129], v[204:205], v[128:129], v[208:209]
	v_pk_fma_f32 v[126:127], v[90:91], v[198:199], v[126:127]
	v_pk_fma_f32 v[128:129], v[92:93], v[200:201], v[128:129]
	global_store_dwordx4 v145, v[126:129], s[82:83] offset:64
	s_nop 1
	global_load_dwordx4 v[126:129], v145, s[82:83] offset:128
	s_waitcnt vmcnt(17)
	v_pk_add_f32 v[134:135], v[134:135], v[166:167] op_sel_hi:[1,0] neg_lo:[0,1] neg_hi:[0,1]
	v_pk_add_f32 v[136:137], v[136:137], v[166:167] op_sel_hi:[1,0] neg_lo:[0,1] neg_hi:[0,1]
	v_pk_mul_f32 v[134:135], v[134:135], v[166:167] op_sel:[0,1]
	v_pk_mul_f32 v[136:137], v[136:137], v[166:167] op_sel:[0,1]
	v_pk_fma_f32 v[134:135], v[202:203], v[134:135], v[206:207]
	v_pk_fma_f32 v[136:137], v[204:205], v[136:137], v[208:209]
	v_pk_fma_f32 v[134:135], v[86:87], v[198:199], v[134:135]
	v_pk_fma_f32 v[136:137], v[88:89], v[200:201], v[136:137]
	global_store_dwordx4 v210, v[134:137], s[82:83] offset:64
	s_nop 1
	global_load_dwordx4 v[134:137], v210, s[82:83] offset:128
	s_waitcnt vmcnt(17)
	v_pk_add_f32 v[138:139], v[138:139], v[168:169] op_sel_hi:[1,0] neg_lo:[0,1] neg_hi:[0,1]
	v_pk_add_f32 v[140:141], v[140:141], v[168:169] op_sel_hi:[1,0] neg_lo:[0,1] neg_hi:[0,1]
	v_pk_mul_f32 v[138:139], v[138:139], v[168:169] op_sel:[0,1]
	v_pk_mul_f32 v[140:141], v[140:141], v[168:169] op_sel:[0,1]
	v_pk_fma_f32 v[138:139], v[202:203], v[138:139], v[206:207]
	v_pk_fma_f32 v[140:141], v[204:205], v[140:141], v[208:209]
	v_pk_fma_f32 v[138:139], v[82:83], v[198:199], v[138:139]
	v_pk_fma_f32 v[140:141], v[84:85], v[200:201], v[140:141]
	global_store_dwordx4 v211, v[138:141], s[82:83] offset:64
	s_nop 1
	global_load_dwordx4 v[138:141], v211, s[82:83] offset:128
	s_waitcnt vmcnt(17)
	v_pk_add_f32 v[146:147], v[146:147], v[170:171] op_sel_hi:[1,0] neg_lo:[0,1] neg_hi:[0,1]
	v_pk_add_f32 v[148:149], v[148:149], v[170:171] op_sel_hi:[1,0] neg_lo:[0,1] neg_hi:[0,1]
	v_pk_mul_f32 v[146:147], v[146:147], v[170:171] op_sel:[0,1]
	v_pk_mul_f32 v[148:149], v[148:149], v[170:171] op_sel:[0,1]
	v_pk_fma_f32 v[146:147], v[202:203], v[146:147], v[206:207]
	v_pk_fma_f32 v[148:149], v[204:205], v[148:149], v[208:209]
	v_pk_fma_f32 v[146:147], v[78:79], v[198:199], v[146:147]
	v_pk_fma_f32 v[148:149], v[80:81], v[200:201], v[148:149]
	global_store_dwordx4 v212, v[146:149], s[82:83] offset:64
	s_nop 1
	global_load_dwordx4 v[146:149], v212, s[82:83] offset:128
	s_waitcnt vmcnt(17)
	v_pk_add_f32 v[150:151], v[150:151], v[172:173] op_sel_hi:[1,0] neg_lo:[0,1] neg_hi:[0,1]
	v_pk_add_f32 v[152:153], v[152:153], v[172:173] op_sel_hi:[1,0] neg_lo:[0,1] neg_hi:[0,1]
	v_pk_mul_f32 v[150:151], v[150:151], v[172:173] op_sel:[0,1]
	v_pk_mul_f32 v[152:153], v[152:153], v[172:173] op_sel:[0,1]
	v_pk_fma_f32 v[150:151], v[202:203], v[150:151], v[206:207]
	v_pk_fma_f32 v[152:153], v[204:205], v[152:153], v[208:209]
	v_pk_fma_f32 v[150:151], v[74:75], v[198:199], v[150:151]
	v_pk_fma_f32 v[152:153], v[76:77], v[200:201], v[152:153]
	global_store_dwordx4 v213, v[150:153], s[82:83] offset:64
	s_nop 1
	global_load_dwordx4 v[150:153], v213, s[82:83] offset:128
	s_waitcnt vmcnt(17)
	v_pk_add_f32 v[154:155], v[154:155], v[174:175] op_sel_hi:[1,0] neg_lo:[0,1] neg_hi:[0,1]
	v_pk_add_f32 v[156:157], v[156:157], v[174:175] op_sel_hi:[1,0] neg_lo:[0,1] neg_hi:[0,1]
	v_pk_mul_f32 v[154:155], v[154:155], v[174:175] op_sel:[0,1]
	v_pk_mul_f32 v[156:157], v[156:157], v[174:175] op_sel:[0,1]
	v_pk_fma_f32 v[154:155], v[202:203], v[154:155], v[206:207]
	v_pk_fma_f32 v[156:157], v[204:205], v[156:157], v[208:209]
	v_pk_fma_f32 v[154:155], v[70:71], v[198:199], v[154:155]
	v_pk_fma_f32 v[156:157], v[72:73], v[200:201], v[156:157]
	global_store_dwordx4 v214, v[154:157], s[82:83] offset:64
	s_nop 1
	global_load_dwordx4 v[154:157], v214, s[82:83] offset:128
	s_waitcnt vmcnt(17)
	v_pk_add_f32 v[158:159], v[158:159], v[176:177] op_sel_hi:[1,0] neg_lo:[0,1] neg_hi:[0,1]
	v_pk_add_f32 v[160:161], v[160:161], v[176:177] op_sel_hi:[1,0] neg_lo:[0,1] neg_hi:[0,1]
	v_pk_mul_f32 v[158:159], v[158:159], v[176:177] op_sel:[0,1]
	v_pk_mul_f32 v[160:161], v[160:161], v[176:177] op_sel:[0,1]
	v_pk_fma_f32 v[158:159], v[202:203], v[158:159], v[206:207]
	v_pk_fma_f32 v[160:161], v[204:205], v[160:161], v[208:209]
	v_pk_fma_f32 v[158:159], v[66:67], v[198:199], v[158:159]
	v_pk_fma_f32 v[160:161], v[68:69], v[200:201], v[160:161]
	global_store_dwordx4 v215, v[158:161], s[82:83] offset:64
	s_nop 1
	global_load_dwordx4 v[158:161], v215, s[82:83] offset:128
	global_load_dwordx4 v[198:201], v216, s[84:85] offset:192
	global_load_dwordx4 v[202:205], v216, s[10:11] offset:192
	global_load_dwordx4 v[206:209], v216, s[80:81] offset:192
	s_waitcnt vmcnt(19)
	v_pk_mul_f32 v[190:191], v[190:191], s[70:71] op_sel_hi:[1,0]
	v_pk_mul_f32 v[192:193], v[192:193], s[70:71] op_sel_hi:[1,0]
	v_pk_mul_f32 v[194:195], v[194:195], s[70:71] op_sel_hi:[1,0]
	v_pk_mul_f32 v[196:197], v[196:197], s[70:71] op_sel_hi:[1,0]
	s_waitcnt vmcnt(17)
	v_pk_add_f32 v[110:111], v[110:111], v[130:131] op_sel_hi:[1,0] neg_lo:[0,1] neg_hi:[0,1]
	v_pk_add_f32 v[112:113], v[112:113], v[130:131] op_sel_hi:[1,0] neg_lo:[0,1] neg_hi:[0,1]
	v_pk_mul_f32 v[110:111], v[110:111], v[130:131] op_sel:[0,1]
	v_pk_mul_f32 v[112:113], v[112:113], v[130:131] op_sel:[0,1]
	v_pk_fma_f32 v[110:111], v[190:191], v[110:111], v[194:195]
	v_pk_fma_f32 v[112:113], v[192:193], v[112:113], v[196:197]
	v_pk_fma_f32 v[110:111], v[62:63], v[186:187], v[110:111]
	v_pk_fma_f32 v[112:113], v[64:65], v[188:189], v[112:113]
	global_store_dwordx4 v133, v[110:113], s[82:83] offset:128
	s_nop 1
	global_load_dwordx4 v[110:113], v133, s[82:83] offset:192
	s_waitcnt vmcnt(17)
	v_pk_add_f32 v[126:127], v[126:127], v[142:143] op_sel_hi:[1,0] neg_lo:[0,1] neg_hi:[0,1]
	v_pk_add_f32 v[128:129], v[128:129], v[142:143] op_sel_hi:[1,0] neg_lo:[0,1] neg_hi:[0,1]
	v_pk_mul_f32 v[126:127], v[126:127], v[142:143] op_sel:[0,1]
	v_pk_mul_f32 v[128:129], v[128:129], v[142:143] op_sel:[0,1]
	v_pk_fma_f32 v[126:127], v[190:191], v[126:127], v[194:195]
	v_pk_fma_f32 v[128:129], v[192:193], v[128:129], v[196:197]
	v_pk_fma_f32 v[126:127], v[58:59], v[186:187], v[126:127]
	v_pk_fma_f32 v[128:129], v[60:61], v[188:189], v[128:129]
	global_store_dwordx4 v145, v[126:129], s[82:83] offset:128
	s_nop 1
	global_load_dwordx4 v[126:129], v145, s[82:83] offset:192
	s_waitcnt vmcnt(17)
	v_pk_add_f32 v[134:135], v[134:135], v[166:167] op_sel_hi:[1,0] neg_lo:[0,1] neg_hi:[0,1]
	v_pk_add_f32 v[136:137], v[136:137], v[166:167] op_sel_hi:[1,0] neg_lo:[0,1] neg_hi:[0,1]
	v_pk_mul_f32 v[134:135], v[134:135], v[166:167] op_sel:[0,1]
	v_pk_mul_f32 v[136:137], v[136:137], v[166:167] op_sel:[0,1]
	v_pk_fma_f32 v[134:135], v[190:191], v[134:135], v[194:195]
	v_pk_fma_f32 v[136:137], v[192:193], v[136:137], v[196:197]
	v_pk_fma_f32 v[134:135], v[54:55], v[186:187], v[134:135]
	v_pk_fma_f32 v[136:137], v[56:57], v[188:189], v[136:137]
	global_store_dwordx4 v210, v[134:137], s[82:83] offset:128
	s_nop 1
	global_load_dwordx4 v[134:137], v210, s[82:83] offset:192
	s_waitcnt vmcnt(17)
	v_pk_add_f32 v[138:139], v[138:139], v[168:169] op_sel_hi:[1,0] neg_lo:[0,1] neg_hi:[0,1]
	v_pk_add_f32 v[140:141], v[140:141], v[168:169] op_sel_hi:[1,0] neg_lo:[0,1] neg_hi:[0,1]
	v_pk_mul_f32 v[138:139], v[138:139], v[168:169] op_sel:[0,1]
	v_pk_mul_f32 v[140:141], v[140:141], v[168:169] op_sel:[0,1]
	v_pk_fma_f32 v[138:139], v[190:191], v[138:139], v[194:195]
	v_pk_fma_f32 v[140:141], v[192:193], v[140:141], v[196:197]
	v_pk_fma_f32 v[138:139], v[50:51], v[186:187], v[138:139]
	v_pk_fma_f32 v[140:141], v[52:53], v[188:189], v[140:141]
	global_store_dwordx4 v211, v[138:141], s[82:83] offset:128
	s_nop 1
	global_load_dwordx4 v[138:141], v211, s[82:83] offset:192
	s_waitcnt vmcnt(17)
	v_pk_add_f32 v[146:147], v[146:147], v[170:171] op_sel_hi:[1,0] neg_lo:[0,1] neg_hi:[0,1]
	v_pk_add_f32 v[148:149], v[148:149], v[170:171] op_sel_hi:[1,0] neg_lo:[0,1] neg_hi:[0,1]
	v_pk_mul_f32 v[146:147], v[146:147], v[170:171] op_sel:[0,1]
	v_pk_mul_f32 v[148:149], v[148:149], v[170:171] op_sel:[0,1]
	v_pk_fma_f32 v[146:147], v[190:191], v[146:147], v[194:195]
	v_pk_fma_f32 v[148:149], v[192:193], v[148:149], v[196:197]
	v_pk_fma_f32 v[146:147], v[46:47], v[186:187], v[146:147]
	v_pk_fma_f32 v[148:149], v[48:49], v[188:189], v[148:149]
	global_store_dwordx4 v212, v[146:149], s[82:83] offset:128
	s_nop 1
	global_load_dwordx4 v[146:149], v212, s[82:83] offset:192
	s_waitcnt vmcnt(17)
	v_pk_add_f32 v[150:151], v[150:151], v[172:173] op_sel_hi:[1,0] neg_lo:[0,1] neg_hi:[0,1]
	v_pk_add_f32 v[152:153], v[152:153], v[172:173] op_sel_hi:[1,0] neg_lo:[0,1] neg_hi:[0,1]
	v_pk_mul_f32 v[150:151], v[150:151], v[172:173] op_sel:[0,1]
	v_pk_mul_f32 v[152:153], v[152:153], v[172:173] op_sel:[0,1]
	v_pk_fma_f32 v[150:151], v[190:191], v[150:151], v[194:195]
	v_pk_fma_f32 v[152:153], v[192:193], v[152:153], v[196:197]
	v_pk_fma_f32 v[150:151], v[42:43], v[186:187], v[150:151]
	v_pk_fma_f32 v[152:153], v[44:45], v[188:189], v[152:153]
	global_store_dwordx4 v213, v[150:153], s[82:83] offset:128
	s_nop 1
	global_load_dwordx4 v[150:153], v213, s[82:83] offset:192
	s_waitcnt vmcnt(17)
	v_pk_add_f32 v[154:155], v[154:155], v[174:175] op_sel_hi:[1,0] neg_lo:[0,1] neg_hi:[0,1]
	v_pk_add_f32 v[156:157], v[156:157], v[174:175] op_sel_hi:[1,0] neg_lo:[0,1] neg_hi:[0,1]
	v_pk_mul_f32 v[154:155], v[154:155], v[174:175] op_sel:[0,1]
	v_pk_mul_f32 v[156:157], v[156:157], v[174:175] op_sel:[0,1]
	v_pk_fma_f32 v[154:155], v[190:191], v[154:155], v[194:195]
	v_pk_fma_f32 v[156:157], v[192:193], v[156:157], v[196:197]
	v_pk_fma_f32 v[154:155], v[38:39], v[186:187], v[154:155]
	v_pk_fma_f32 v[156:157], v[40:41], v[188:189], v[156:157]
	global_store_dwordx4 v214, v[154:157], s[82:83] offset:128
	s_nop 1
	global_load_dwordx4 v[154:157], v214, s[82:83] offset:192
	s_waitcnt vmcnt(17)
	v_pk_add_f32 v[158:159], v[158:159], v[176:177] op_sel_hi:[1,0] neg_lo:[0,1] neg_hi:[0,1]
	v_pk_add_f32 v[160:161], v[160:161], v[176:177] op_sel_hi:[1,0] neg_lo:[0,1] neg_hi:[0,1]
	v_pk_mul_f32 v[158:159], v[158:159], v[176:177] op_sel:[0,1]
	v_pk_mul_f32 v[160:161], v[160:161], v[176:177] op_sel:[0,1]
	v_pk_fma_f32 v[158:159], v[190:191], v[158:159], v[194:195]
	v_pk_fma_f32 v[160:161], v[192:193], v[160:161], v[196:197]
	v_pk_fma_f32 v[158:159], v[34:35], v[186:187], v[158:159]
	v_pk_fma_f32 v[160:161], v[36:37], v[188:189], v[160:161]
	global_store_dwordx4 v215, v[158:161], s[82:83] offset:128
	s_nop 1
	global_load_dwordx4 v[158:161], v215, s[82:83] offset:192
	s_waitcnt vmcnt(16)
	v_pk_mul_f32 v[202:203], v[202:203], s[70:71] op_sel_hi:[1,0]
	v_pk_mul_f32 v[204:205], v[204:205], s[70:71] op_sel_hi:[1,0]
	v_pk_mul_f32 v[206:207], v[206:207], s[70:71] op_sel_hi:[1,0]
	v_pk_mul_f32 v[208:209], v[208:209], s[70:71] op_sel_hi:[1,0]
	s_waitcnt vmcnt(14)
	v_pk_add_f32 v[110:111], v[110:111], v[130:131] op_sel_hi:[1,0] neg_lo:[0,1] neg_hi:[0,1]
	v_pk_add_f32 v[112:113], v[112:113], v[130:131] op_sel_hi:[1,0] neg_lo:[0,1] neg_hi:[0,1]
	v_pk_mul_f32 v[110:111], v[110:111], v[130:131] op_sel:[0,1]
	v_pk_mul_f32 v[112:113], v[112:113], v[130:131] op_sel:[0,1]
	v_pk_fma_f32 v[110:111], v[202:203], v[110:111], v[206:207]
	v_pk_fma_f32 v[112:113], v[204:205], v[112:113], v[208:209]
	v_pk_fma_f32 v[110:111], v[30:31], v[198:199], v[110:111]
	v_pk_fma_f32 v[112:113], v[32:33], v[200:201], v[112:113]
	global_store_dwordx4 v133, v[110:113], s[82:83] offset:192
	s_waitcnt vmcnt(13)
	v_pk_add_f32 v[126:127], v[126:127], v[142:143] op_sel_hi:[1,0] neg_lo:[0,1] neg_hi:[0,1]
	v_pk_add_f32 v[128:129], v[128:129], v[142:143] op_sel_hi:[1,0] neg_lo:[0,1] neg_hi:[0,1]
	v_pk_mul_f32 v[126:127], v[126:127], v[142:143] op_sel:[0,1]
	v_pk_mul_f32 v[128:129], v[128:129], v[142:143] op_sel:[0,1]
	v_pk_fma_f32 v[126:127], v[202:203], v[126:127], v[206:207]
	v_pk_fma_f32 v[128:129], v[204:205], v[128:129], v[208:209]
	v_pk_fma_f32 v[126:127], v[26:27], v[198:199], v[126:127]
	v_pk_fma_f32 v[128:129], v[28:29], v[200:201], v[128:129]
	global_store_dwordx4 v145, v[126:129], s[82:83] offset:192
	s_waitcnt vmcnt(12)
	v_pk_add_f32 v[134:135], v[134:135], v[166:167] op_sel_hi:[1,0] neg_lo:[0,1] neg_hi:[0,1]
	v_pk_add_f32 v[136:137], v[136:137], v[166:167] op_sel_hi:[1,0] neg_lo:[0,1] neg_hi:[0,1]
	v_pk_mul_f32 v[134:135], v[134:135], v[166:167] op_sel:[0,1]
	v_pk_mul_f32 v[136:137], v[136:137], v[166:167] op_sel:[0,1]
	v_pk_fma_f32 v[134:135], v[202:203], v[134:135], v[206:207]
	v_pk_fma_f32 v[136:137], v[204:205], v[136:137], v[208:209]
	v_pk_fma_f32 v[134:135], v[22:23], v[198:199], v[134:135]
	v_pk_fma_f32 v[136:137], v[24:25], v[200:201], v[136:137]
	global_store_dwordx4 v210, v[134:137], s[82:83] offset:192
	s_waitcnt vmcnt(11)
	v_pk_add_f32 v[138:139], v[138:139], v[168:169] op_sel_hi:[1,0] neg_lo:[0,1] neg_hi:[0,1]
	v_pk_add_f32 v[140:141], v[140:141], v[168:169] op_sel_hi:[1,0] neg_lo:[0,1] neg_hi:[0,1]
	v_pk_mul_f32 v[138:139], v[138:139], v[168:169] op_sel:[0,1]
	v_pk_mul_f32 v[140:141], v[140:141], v[168:169] op_sel:[0,1]
	v_pk_fma_f32 v[138:139], v[202:203], v[138:139], v[206:207]
	v_pk_fma_f32 v[140:141], v[204:205], v[140:141], v[208:209]
	v_pk_fma_f32 v[138:139], v[18:19], v[198:199], v[138:139]
	v_pk_fma_f32 v[140:141], v[20:21], v[200:201], v[140:141]
	global_store_dwordx4 v211, v[138:141], s[82:83] offset:192
	s_waitcnt vmcnt(10)
	v_pk_add_f32 v[146:147], v[146:147], v[170:171] op_sel_hi:[1,0] neg_lo:[0,1] neg_hi:[0,1]
	v_pk_add_f32 v[148:149], v[148:149], v[170:171] op_sel_hi:[1,0] neg_lo:[0,1] neg_hi:[0,1]
	v_pk_mul_f32 v[146:147], v[146:147], v[170:171] op_sel:[0,1]
	v_pk_mul_f32 v[148:149], v[148:149], v[170:171] op_sel:[0,1]
	v_pk_fma_f32 v[146:147], v[202:203], v[146:147], v[206:207]
	v_pk_fma_f32 v[148:149], v[204:205], v[148:149], v[208:209]
	v_pk_fma_f32 v[146:147], v[14:15], v[198:199], v[146:147]
	v_pk_fma_f32 v[148:149], v[16:17], v[200:201], v[148:149]
	global_store_dwordx4 v212, v[146:149], s[82:83] offset:192
	s_waitcnt vmcnt(9)
	v_pk_add_f32 v[150:151], v[150:151], v[172:173] op_sel_hi:[1,0] neg_lo:[0,1] neg_hi:[0,1]
	v_pk_add_f32 v[152:153], v[152:153], v[172:173] op_sel_hi:[1,0] neg_lo:[0,1] neg_hi:[0,1]
	v_pk_mul_f32 v[150:151], v[150:151], v[172:173] op_sel:[0,1]
	v_pk_mul_f32 v[152:153], v[152:153], v[172:173] op_sel:[0,1]
	v_pk_fma_f32 v[150:151], v[202:203], v[150:151], v[206:207]
	v_pk_fma_f32 v[152:153], v[204:205], v[152:153], v[208:209]
	v_pk_fma_f32 v[150:151], v[10:11], v[198:199], v[150:151]
	v_pk_fma_f32 v[152:153], v[12:13], v[200:201], v[152:153]
	global_store_dwordx4 v213, v[150:153], s[82:83] offset:192
	s_waitcnt vmcnt(8)
	v_pk_add_f32 v[154:155], v[154:155], v[174:175] op_sel_hi:[1,0] neg_lo:[0,1] neg_hi:[0,1]
	v_pk_add_f32 v[156:157], v[156:157], v[174:175] op_sel_hi:[1,0] neg_lo:[0,1] neg_hi:[0,1]
	v_pk_mul_f32 v[154:155], v[154:155], v[174:175] op_sel:[0,1]
	v_pk_mul_f32 v[156:157], v[156:157], v[174:175] op_sel:[0,1]
	v_pk_fma_f32 v[154:155], v[202:203], v[154:155], v[206:207]
	v_pk_fma_f32 v[156:157], v[204:205], v[156:157], v[208:209]
	v_pk_fma_f32 v[154:155], v[6:7], v[198:199], v[154:155]
	v_pk_fma_f32 v[156:157], v[8:9], v[200:201], v[156:157]
	global_store_dwordx4 v214, v[154:157], s[82:83] offset:192
	s_waitcnt vmcnt(7)
	v_pk_add_f32 v[158:159], v[158:159], v[176:177] op_sel_hi:[1,0] neg_lo:[0,1] neg_hi:[0,1]
	v_pk_add_f32 v[160:161], v[160:161], v[176:177] op_sel_hi:[1,0] neg_lo:[0,1] neg_hi:[0,1]
	v_pk_mul_f32 v[158:159], v[158:159], v[176:177] op_sel:[0,1]
	v_pk_mul_f32 v[160:161], v[160:161], v[176:177] op_sel:[0,1]
	v_pk_fma_f32 v[158:159], v[202:203], v[158:159], v[206:207]
	v_pk_fma_f32 v[160:161], v[204:205], v[160:161], v[208:209]
	v_pk_fma_f32 v[158:159], v[2:3], v[198:199], v[158:159]
	v_pk_fma_f32 v[160:161], v[4:5], v[200:201], v[160:161]
	global_store_dwordx4 v215, v[158:161], s[82:83] offset:192
	s_add_i32 s60, s60, s30
	s_cmpk_gt_i32 s60, 0xff
	s_cbranch_scc1 .LBB0_1036
